# MFMA K loops of P2a S3 and P2b S3 request their LDS fragments ahead (counted waits) instead of read+drain per step; P2b S3 fragment blocks software-pipelined by one block on two register sets
# baseline (speedup 1.0000x reference)
; #define LAS __attribute__((address_space(3)))
; #define MFMA32(a, b, c) __builtin_amdgcn_mfma_f32_32x32x16_bf16((a), (b), (c), 0, 0, 0)
; __device__ __forceinline__ void gdn_prep_phase(LAS unsigned char* lds, const GdnPrepArgs& A, int bid, int G, const unsigned char* zero_page) {
;     ...
;     {
;         const int which = w >> 2, rt = (w >> 1) & 1, ct = w & 1, r = lane & 31, hh = lane >> 5;
;         const LAS unsigned char* ia = lds + (which ? L_QN : L_KN) + (32 * rt + r) * QS_ + 16 * hh;
;         const LAS unsigned char* ib = lds + L_KN + (32 * ct + r) * QS_ + 16 * hh;
;         f32x16 acc = zero16();
; #pragma unroll
;         for (int ks = 0; ks < 8; ++ks) acc = MFMA32(*(const LAS bf16x8*)(ia + 32 * ks), *(const LAS bf16x8*)(ib + 32 * ks), acc);
;         const LAS float* sc = (const LAS float*)(lds + L_SC);
;         const int j = 32 * ct + r; const float gfj = sc[j], gbj = sc[64 + j];
; #pragma unroll
;         for (int reg = 0; reg < 16; ++reg) {
;             const int i = 32 * rt + (reg & 3) + 8 * (reg >> 2) + 4 * hh; const float val = acc[reg];
;             const float ef = __expf(sc[i] - gfj), eb = __expf(sc[64 + i] - gbj);
.LBB0_209:
	s_nop 0
	ds_read2st64_b32 v[136:137], v72 offset1:1
	ds_read2st64_b32 v[138:139], v74 offset1:1
	ds_read2st64_b32 v[140:141], v76 offset1:1
	ds_read2st64_b32 v[142:143], v78 offset1:1
	ds_read2st64_b32 v[144:145], v80 offset1:1
	ds_read2st64_b32 v[146:147], v82 offset1:1
	ds_read2st64_b32 v[148:149], v84 offset1:1
	ds_read2st64_b32 v[150:151], v86 offset1:1
	ds_read2st64_b32 v[152:153], v88 offset1:1
	ds_read2st64_b32 v[154:155], v90 offset1:1
	ds_read2st64_b32 v[156:157], v92 offset1:1
	ds_read2st64_b32 v[158:159], v94 offset1:1
	ds_read2st64_b32 v[160:161], v96 offset1:1
	ds_read2st64_b32 v[162:163], v98 offset1:1
	ds_read2st64_b32 v[174:175], v100 offset1:1
	ds_read2st64_b32 v[176:177], v102 offset1:1
	ds_read2st64_b32 v[178:179], v72 offset0:2 offset1:3
	ds_read2st64_b32 v[180:181], v74 offset0:2 offset1:3
	ds_read2st64_b32 v[182:183], v76 offset0:2 offset1:3
	ds_read2st64_b32 v[230:231], v78 offset0:2 offset1:3
	ds_read2st64_b32 v[232:233], v80 offset0:2 offset1:3
	ds_read2st64_b32 v[234:235], v82 offset0:2 offset1:3
	ds_read2st64_b32 v[236:237], v84 offset0:2 offset1:3
	ds_read2st64_b32 v[238:239], v86 offset0:2 offset1:3
	ds_read2st64_b32 v[240:241], v88 offset0:2 offset1:3
	ds_read2st64_b32 v[242:243], v90 offset0:2 offset1:3
	ds_read2st64_b32 v[244:245], v92 offset0:2 offset1:3
	ds_read2st64_b32 v[248:249], v94 offset0:2 offset1:3
	ds_read_b128 v[2:5], v190
	ds_read_b128 v[6:9], v191
	ds_read_b128 v[32:35], v190 offset:32
	ds_read_b128 v[36:39], v191 offset:32
	ds_read_b128 v[46:49], v190 offset:64
	ds_read_b128 v[208:211], v191 offset:64
	ds_read_b128 v[212:215], v190 offset:96
	ds_read_b128 v[216:219], v191 offset:96
	ds_read_b128 v[220:223], v190 offset:128
	ds_read_b128 v[40:43], v191 offset:128
	s_mov_b64 s[46:47], -1
	s_and_b64 vcc, exec, s[4:5]
	s_waitcnt lgkmcnt(8)
	v_mfma_f32_32x32x16_bf16 v[2:17], v[2:5], v[6:9], 0
	s_waitcnt lgkmcnt(6)
	v_mfma_f32_32x32x16_bf16 v[2:17], v[32:35], v[36:39], v[2:17]
	ds_read_b128 v[32:35], v190 offset:160
	ds_read_b128 v[36:39], v191 offset:160
	s_waitcnt lgkmcnt(6)
	v_mfma_f32_32x32x16_bf16 v[2:17], v[46:49], v[208:211], v[2:17]
	ds_read_b128 v[46:49], v190 offset:192
	ds_read_b128 v[208:211], v191 offset:192
	s_waitcnt lgkmcnt(6)
	v_mfma_f32_32x32x16_bf16 v[2:17], v[212:215], v[216:219], v[2:17]
	ds_read_b128 v[212:215], v190 offset:224
	ds_read_b128 v[216:219], v191 offset:224
	s_waitcnt lgkmcnt(6)
	v_mfma_f32_32x32x16_bf16 v[2:17], v[220:223], v[40:43], v[2:17]
	s_waitcnt lgkmcnt(4)
	v_mfma_f32_32x32x16_bf16 v[2:17], v[32:35], v[36:39], v[2:17]
	ds_read2st64_b32 v[32:33], v55 offset1:1
	s_waitcnt lgkmcnt(3)
	v_mfma_f32_32x32x16_bf16 v[2:17], v[46:49], v[208:211], v[2:17]
	s_waitcnt lgkmcnt(1)
	v_mfma_f32_32x32x16_bf16 v[2:17], v[212:215], v[216:219], v[2:17]
	s_waitcnt lgkmcnt(0)
	v_sub_f32_e32 v38, v136, v32
	v_mul_f32_e32 v38, 0x3fb8aa3b, v38
	v_sub_f32_e32 v34, v137, v33
	v_mul_f32_e32 v34, 0x3fb8aa3b, v34
	v_exp_f32_e32 v35, v38
	v_exp_f32_e32 v34, v34
	s_cbranch_vccz .LBB0_211
	s_nop 6
	v_mul_f32_e32 v36, 0x3db504f3, v2
	v_mul_f32_e32 v37, v36, v35
	v_mul_f32_e32 v36, v36, v34
	v_readlane_b32 s46, v255, 15
	v_cvt_pk_bf16_f32 v37, v37, s0
	v_cvt_pk_bf16_f32 v36, v36, s0
	v_readlane_b32 s47, v255, 16
	v_cndmask_b32_e64 v37, v37, 0, s[6:7]
	ds_write_b16 v228, v37
	v_cndmask_b32_e64 v36, v36, 0, s[46:47]
	ds_write_b16 v229, v36
	s_mov_b64 s[46:47], 0

; #define LAS __attribute__((address_space(3)))
; __device__ __forceinline__ v4u frag_tr_nat(const LAS unsigned char* img, int st, int colbase, int ks, int lane) {
;     const int r = lane & 31, hh = lane >> 5; const LAS unsigned char* p = img + (16 * ks + 8 * hh) * st + (colbase + r) * 2;
;     unsigned short e[8];
; #pragma unroll
;     for (int j = 0; j < 8; ++j) e[j] = *(const LAS unsigned short*)(p + j * st);
;     return (v4u){(unsigned)e[0] | ((unsigned)e[1] << 16), (unsigned)e[2] | ((unsigned)e[3] << 16), (unsigned)e[4] | ((unsigned)e[5] << 16), (unsigned)e[6] | ((unsigned)e[7] << 16)};
; __device__ __forceinline__ void gla_prep_phase(LAS unsigned char* lds, const GlaPrepArgs& A, int bid, int G) {
;     ...
;         for (int k = 0; k < 16; ++k) {
;             const int wh = k >> 2, b = b0 + 4 * (k & 3); v4u f; int off;
;             if (wh == 0)      { f = gdn::frag_rm_perm(lds + L_QGF, QS_, b >> 3, b & 7, lane); off = B_QGF; }
;             else if (wh == 1) { f = gdn::frag_rm_perm(lds + L_QGB, QS_, b >> 3, b & 7, lane); off = B_QGB; }
;             else if (wh == 2) { f = frag_tr_nat(lds + L_KDF, QS_, 32 * (b >> 2), b & 3, lane); off = B_KDTF; }
;             else              { f = frag_tr_nat(lds + L_KDB, QS_, 32 * (b >> 2), b & 3, lane); off = B_KDTB; }
;             *(v4u*)(blob + off + b * 1024 + lane * 16) = f;
;         }
.LBB0_429:
	v_add_u32_e32 v180, 0x2000, v115
	ds_read2_b64 v[180:183], v180 offset1:2
	v_add_u32_e32 v190, 0x2000, v116
	ds_read2_b64 v[190:193], v190 offset1:2
	s_add_u32 s80, s88, s34
	s_addc_u32 s81, s89, 0
	v_lshl_add_u64 v[200:201], s[80:81], 0, v[88:89]
	s_add_u32 s80, s88, s84
	s_waitcnt lgkmcnt(1)
	global_store_dwordx4 v[200:201], v[180:183], off
	s_nop 1
	v_add_u32_e32 v180, 0x2000, v117
	ds_read2_b64 v[180:183], v180 offset1:2
	s_addc_u32 s81, s89, 0
	v_lshl_add_u64 v[202:203], s[80:81], 0, v[88:89]
	s_add_u32 s80, s88, s85
	s_addc_u32 s81, s89, 0
	s_waitcnt lgkmcnt(1)
	global_store_dwordx4 v[202:203], v[190:193], off
	s_nop 1
	v_add_u32_e32 v190, 0x2000, v118
	ds_read2_b64 v[190:193], v190 offset1:2
	s_nop 1
	v_lshl_add_u64 v[200:201], s[80:81], 0, v[88:89]
	s_add_u32 s80, s88, s86
	s_addc_u32 s81, s89, 0
	s_add_u32 s91, s88, 0x4000
	s_waitcnt lgkmcnt(1)
	global_store_dwordx4 v[200:201], v[180:183], off
	s_nop 1
	v_add_u32_e32 v180, 0xe800, v115
	ds_read2_b64 v[180:183], v180 offset0:128 offset1:130
	v_lshl_add_u64 v[202:203], s[80:81], 0, v[88:89]
	s_addc_u32 s92, s89, 0
	s_add_u32 s80, s91, s34
	s_addc_u32 s81, s92, 0
	s_waitcnt lgkmcnt(1)
	global_store_dwordx4 v[202:203], v[190:193], off
	s_nop 1
	v_add_u32_e32 v190, 0xe800, v116
	ds_read2_b64 v[190:193], v190 offset0:128 offset1:130
	s_nop 1
	v_lshl_add_u64 v[200:201], s[80:81], 0, v[88:89]
	s_add_u32 s80, s91, s84
	s_addc_u32 s81, s92, 0
	s_waitcnt lgkmcnt(1)
	global_store_dwordx4 v[200:201], v[180:183], off
	s_nop 1
	v_add_u32_e32 v180, 0xe800, v117
	ds_read2_b64 v[180:183], v180 offset0:128 offset1:130
	v_lshl_add_u64 v[202:203], s[80:81], 0, v[88:89]
	s_nop 0
	s_add_u32 s80, s91, s85
	s_addc_u32 s81, s92, 0
	s_waitcnt lgkmcnt(1)
	global_store_dwordx4 v[202:203], v[190:193], off
	s_nop 1
	v_add_u32_e32 v190, 0xe800, v118
	ds_read2_b64 v[190:193], v190 offset0:128 offset1:130
	s_nop 1
	v_lshl_add_u64 v[200:201], s[80:81], 0, v[88:89]
	s_add_u32 s80, s91, s86
	s_addc_u32 s81, s92, 0
	s_add_u32 s91, s88, 0x8400
	s_waitcnt lgkmcnt(1)
	global_store_dwordx4 v[200:201], v[180:183], off
	s_nop 1
	v_add_u32_e32 v180, v101, v103
	ds_read_u16 v184, v180 offset:43008
	ds_read_u16 v185, v180 offset:43280
	ds_read_u16 v181, v180 offset:43552
	ds_read_u16 v186, v180 offset:43824
	ds_read_u16 v182, v180 offset:44096
	ds_read_u16 v187, v180 offset:44368
	ds_read_u16 v183, v180 offset:44640
	ds_read_u16 v180, v180 offset:44912
	v_lshl_add_u64 v[202:203], s[80:81], 0, v[88:89]
	s_addc_u32 s92, s89, 0
	s_add_u32 s80, s91, s34
	s_addc_u32 s81, s92, 0
	s_waitcnt lgkmcnt(8)
	global_store_dwordx4 v[202:203], v[190:193], off
	s_nop 1
	v_add_u32_e32 v190, v101, v104
	ds_read_u16 v194, v190 offset:43008
	ds_read_u16 v195, v190 offset:43280
	ds_read_u16 v191, v190 offset:43552
	ds_read_u16 v196, v190 offset:43824
	ds_read_u16 v192, v190 offset:44096
	ds_read_u16 v197, v190 offset:44368
	ds_read_u16 v193, v190 offset:44640
	ds_read_u16 v190, v190 offset:44912
	s_nop 1
	s_waitcnt lgkmcnt(12)
	v_perm_b32 v181, v186, v181, s33
	s_waitcnt lgkmcnt(10)
	v_perm_b32 v182, v187, v182, s33
	s_waitcnt lgkmcnt(8)
	v_perm_b32 v183, v180, v183, s33
	v_perm_b32 v180, v185, v184, s33
	v_lshl_add_u64 v[200:201], s[80:81], 0, v[88:89]
	global_store_dwordx4 v[200:201], v[180:183], off
	s_nop 1
	v_add_u32_e32 v180, v101, v105
	ds_read_u16 v184, v180 offset:43008
	ds_read_u16 v185, v180 offset:43280
	ds_read_u16 v181, v180 offset:43552
	ds_read_u16 v186, v180 offset:43824
	ds_read_u16 v182, v180 offset:44096
	ds_read_u16 v187, v180 offset:44368
	ds_read_u16 v183, v180 offset:44640
	ds_read_u16 v180, v180 offset:44912
	s_add_u32 s80, s91, s84
	s_addc_u32 s81, s92, 0
	s_waitcnt lgkmcnt(12)
	v_perm_b32 v191, v196, v191, s33
	s_waitcnt lgkmcnt(10)
	v_perm_b32 v192, v197, v192, s33
	s_waitcnt lgkmcnt(8)
	v_perm_b32 v193, v190, v193, s33
	v_perm_b32 v190, v195, v194, s33
	v_lshl_add_u64 v[202:203], s[80:81], 0, v[88:89]
	global_store_dwordx4 v[202:203], v[190:193], off
	s_nop 1
	v_add_u32_e32 v190, v101, v106
	ds_read_u16 v194, v190 offset:43008
	ds_read_u16 v195, v190 offset:43280
	ds_read_u16 v191, v190 offset:43552
	ds_read_u16 v196, v190 offset:43824
	ds_read_u16 v192, v190 offset:44096
	ds_read_u16 v197, v190 offset:44368
	ds_read_u16 v193, v190 offset:44640
	ds_read_u16 v190, v190 offset:44912
	s_add_u32 s80, s91, s85
	s_addc_u32 s81, s92, 0
	s_waitcnt lgkmcnt(12)
	v_perm_b32 v181, v186, v181, s33
	s_waitcnt lgkmcnt(10)
	v_perm_b32 v182, v187, v182, s33
	s_waitcnt lgkmcnt(8)
	v_perm_b32 v183, v180, v183, s33
	v_perm_b32 v180, v185, v184, s33
	v_lshl_add_u64 v[200:201], s[80:81], 0, v[88:89]
	global_store_dwordx4 v[200:201], v[180:183], off
	s_nop 1
	v_add_u32_e32 v180, v102, v103
	ds_read_u16 v184, v180
	ds_read_u16 v185, v180 offset:272
	ds_read_u16 v181, v180 offset:544
	ds_read_u16 v186, v180 offset:816
	ds_read_u16 v182, v180 offset:1088
	ds_read_u16 v187, v180 offset:1360
	ds_read_u16 v183, v180 offset:1632
	ds_read_u16 v180, v180 offset:1904
	s_add_u32 s80, s91, s86
	s_addc_u32 s81, s92, 0
	s_waitcnt lgkmcnt(12)
	v_perm_b32 v191, v196, v191, s33
	s_add_u32 s88, s88, 0xc400
	s_waitcnt lgkmcnt(10)
	v_perm_b32 v192, v197, v192, s33
	s_addc_u32 s89, s89, 0
	s_waitcnt lgkmcnt(8)
	v_perm_b32 v193, v190, v193, s33
	v_perm_b32 v190, v195, v194, s33
	v_lshl_add_u64 v[202:203], s[80:81], 0, v[88:89]
	global_store_dwordx4 v[202:203], v[190:193], off
	s_nop 1
	v_add_u32_e32 v190, v102, v104
	ds_read_u16 v194, v190
	ds_read_u16 v195, v190 offset:272
	ds_read_u16 v191, v190 offset:544
	ds_read_u16 v196, v190 offset:816
	ds_read_u16 v192, v190 offset:1088
	ds_read_u16 v197, v190 offset:1360
	ds_read_u16 v193, v190 offset:1632
	ds_read_u16 v190, v190 offset:1904
	s_add_u32 s80, s88, s34
	s_addc_u32 s81, s89, 0
	s_waitcnt lgkmcnt(12)
; #define LAS __attribute__((address_space(3)))
; #define MFMA32(a, b, c) __builtin_amdgcn_mfma_f32_32x32x16_bf16((a), (b), (c), 0, 0, 0)
; __device__ __forceinline__ unsigned pkbf(float a, float b) { bf16x2_t v = __builtin_convertvector((f32x2_t){a, b}, bf16x2_t); return __builtin_bit_cast(unsigned, v); }
; __device__ __forceinline__ void gla_prep_phase(LAS unsigned char* lds, const GlaPrepArgs& A, int bid, int G) {
;     ...
;     if (w < 4) {
;         const int rt = w >> 1, ct = w & 1, r = lane & 31, hh = lane >> 5;
;         f32x16 af = zero16(), ab = zero16();
;         if (rt >= ct) { const LAS unsigned char* ia = lds + L_QGF + (32 * rt + r) * QS_ + 16 * hh; const LAS unsigned char* ib = lds + L_KGF + (32 * ct + r) * QS_ + 16 * hh;
; #pragma unroll
;             for (int ks = 0; ks < 8; ++ks) af = MFMA32(*(const LAS bf16x8*)(ia + 32 * ks), *(const LAS bf16x8*)(ib + 32 * ks), af); }
;         if (rt <= ct) { const LAS unsigned char* ia = lds + L_QGB + (32 * rt + r) * QS_ + 16 * hh; const LAS unsigned char* ib = lds + L_KGB + (32 * ct + r) * QS_ + 16 * hh;
; #pragma unroll
;             for (int ks = 0; ks < 8; ++ks) ab = MFMA32(*(const LAS bf16x8*)(ia + 32 * ks), *(const LAS bf16x8*)(ib + 32 * ks), ab); }
;         const int j = 32 * ct + r;
; #pragma unroll
;         for (int reg = 0; reg < 16; ++reg) { const int i = 32 * rt + (reg & 3) + 8 * (reg >> 2) + 4 * hh;
;             const float val = (i >= j ? af[reg] : 0.f) + (i <= j ? ab[reg] : 0.f);
;             *(LAS unsigned short*)(lds + L_AS + i * AS_ + j * 2) = (unsigned short)(pkbf(val, 0.f) & 0xffffu); }
;     } else {
;         const int b0 = w - 4;
; #pragma unroll
;         for (int k = 0; k < 16; ++k) {
;             const int wh = k >> 2, b = b0 + 4 * (k & 3); v4u f; int off;
;             if (wh == 0)      { f = gdn::frag_rm_perm(lds + L_QGF, QS_, b >> 3, b & 7, lane); off = B_QGF; }
;             else if (wh == 1) { f = gdn::frag_rm_perm(lds + L_QGB, QS_, b >> 3, b & 7, lane); off = B_QGB; }
;             else if (wh == 2) { f = frag_tr_nat(lds + L_KDF, QS_, 32 * (b >> 2), b & 3, lane); off = B_KDTF; }
;             else              { f = frag_tr_nat(lds + L_KDB, QS_, 32 * (b >> 2), b & 3, lane); off = B_KDTB; }
;             *(v4u*)(blob + off + b * 1024 + lane * 16) = f;
;         }
	v_perm_b32 v181, v186, v181, s33
	s_waitcnt lgkmcnt(10)
	v_perm_b32 v182, v187, v182, s33
	s_waitcnt lgkmcnt(8)
	v_perm_b32 v183, v180, v183, s33
	v_perm_b32 v180, v185, v184, s33
	v_lshl_add_u64 v[200:201], s[80:81], 0, v[88:89]
	global_store_dwordx4 v[200:201], v[180:183], off
	s_nop 1
	v_add_u32_e32 v180, v102, v105
	ds_read_u16 v184, v180
	ds_read_u16 v185, v180 offset:272
	ds_read_u16 v181, v180 offset:544
	ds_read_u16 v186, v180 offset:816
	ds_read_u16 v182, v180 offset:1088
	ds_read_u16 v187, v180 offset:1360
	ds_read_u16 v183, v180 offset:1632
	ds_read_u16 v180, v180 offset:1904
	s_add_u32 s80, s88, s84
	s_addc_u32 s81, s89, 0
	s_waitcnt lgkmcnt(12)
	v_perm_b32 v191, v196, v191, s33
	s_waitcnt lgkmcnt(10)
	v_perm_b32 v192, v197, v192, s33
	s_waitcnt lgkmcnt(8)
	v_perm_b32 v193, v190, v193, s33
	v_perm_b32 v190, v195, v194, s33
	v_lshl_add_u64 v[202:203], s[80:81], 0, v[88:89]
	global_store_dwordx4 v[202:203], v[190:193], off
	s_nop 1
	v_add_u32_e32 v190, v102, v106
	ds_read_u16 v194, v190
	ds_read_u16 v195, v190 offset:272
	ds_read_u16 v191, v190 offset:544
	ds_read_u16 v196, v190 offset:816
	ds_read_u16 v192, v190 offset:1088
	ds_read_u16 v197, v190 offset:1360
	ds_read_u16 v193, v190 offset:1632
	ds_read_u16 v190, v190 offset:1904
	s_add_u32 s80, s88, s85
	s_addc_u32 s81, s89, 0
	s_waitcnt lgkmcnt(12)
	v_perm_b32 v181, v186, v181, s33
	s_waitcnt lgkmcnt(10)
	v_perm_b32 v182, v187, v182, s33
	s_waitcnt lgkmcnt(8)
	v_perm_b32 v183, v180, v183, s33
	v_perm_b32 v180, v185, v184, s33
	v_lshl_add_u64 v[200:201], s[80:81], 0, v[88:89]
	global_store_dwordx4 v[200:201], v[180:183], off
	s_add_u32 s80, s88, s86
	s_addc_u32 s81, s89, 0
	s_waitcnt lgkmcnt(4)
	v_perm_b32 v191, v196, v191, s33
	s_waitcnt lgkmcnt(2)
	v_perm_b32 v192, v197, v192, s33
	s_waitcnt lgkmcnt(0)
	v_perm_b32 v193, v190, v193, s33
	v_perm_b32 v190, v195, v194, s33
	v_lshl_add_u64 v[202:203], s[80:81], 0, v[88:89]
	global_store_dwordx4 v[202:203], v[190:193], off
	s_cbranch_execnz .LBB0_422
.LBB0_430:
	v_readlane_b32 s80, v254, 53
	v_readlane_b32 s81, v254, 54
	v_mov_b32_e32 v2, 0
	s_andn2_b64 vcc, exec, s[80:81]
	v_mov_b32_e32 v18, 0
	v_mov_b32_e32 v19, 0
	v_mov_b32_e32 v20, 0
	v_mov_b32_e32 v21, 0
	v_mov_b32_e32 v22, 0
	v_mov_b32_e32 v23, 0
	v_mov_b32_e32 v24, 0
	v_mov_b32_e32 v25, 0
	v_mov_b32_e32 v26, 0
	v_mov_b32_e32 v27, 0
	v_mov_b32_e32 v28, 0
	v_mov_b32_e32 v29, 0
	v_mov_b32_e32 v30, 0
	v_mov_b32_e32 v31, 0
	v_mov_b32_e32 v32, 0
	v_mov_b32_e32 v33, 0
	s_cbranch_vccnz .LBB0_432
	ds_read_b128 v[180:183], v124 offset:8192
	ds_read_b128 v[184:187], v119 offset:25600
	ds_read_b128 v[188:191], v124 offset:8224
	ds_read_b128 v[192:195], v119 offset:25632
	ds_read_b128 v[196:199], v124 offset:8256
	ds_read_b128 v[200:203], v119 offset:25664
	ds_read_b128 v[204:207], v124 offset:8288
	ds_read_b128 v[208:211], v119 offset:25696
	ds_read_b128 v[212:215], v124 offset:8320
	ds_read_b128 v[216:219], v119 offset:25728
	ds_read_b128 v[220:223], v124 offset:8352
	ds_read_b128 v[224:227], v119 offset:25760
	ds_read_b128 v[228:231], v124 offset:8384
	ds_read_b128 v[232:235], v119 offset:25792
	ds_read_b128 v[236:239], v124 offset:8416
	ds_read_b128 v[240:243], v119 offset:25824
	s_waitcnt lgkmcnt(14)
	v_mfma_f32_32x32x16_bf16 v[18:33], v[180:183], v[184:187], 0
	s_waitcnt lgkmcnt(12)
	v_mfma_f32_32x32x16_bf16 v[18:33], v[188:191], v[192:195], v[18:33]
	s_waitcnt lgkmcnt(10)
	v_mfma_f32_32x32x16_bf16 v[18:33], v[196:199], v[200:203], v[18:33]
	s_waitcnt lgkmcnt(8)
	v_mfma_f32_32x32x16_bf16 v[18:33], v[204:207], v[208:211], v[18:33]
	s_waitcnt lgkmcnt(6)
	v_mfma_f32_32x32x16_bf16 v[18:33], v[212:215], v[216:219], v[18:33]
	s_waitcnt lgkmcnt(4)
	v_mfma_f32_32x32x16_bf16 v[18:33], v[220:223], v[224:227], v[18:33]
	s_waitcnt lgkmcnt(2)
	v_mfma_f32_32x32x16_bf16 v[18:33], v[228:231], v[232:235], v[18:33]
	s_waitcnt lgkmcnt(0)
	v_mfma_f32_32x32x16_bf16 v[18:33], v[236:239], v[240:243], v[18:33]
.LBB0_432:
	v_readlane_b32 s80, v254, 57
	v_readlane_b32 s81, v254, 58
	s_andn2_b64 vcc, exec, s[80:81]
	v_mov_b32_e32 v3, 0
	v_mov_b32_e32 v4, 0
	v_mov_b32_e32 v5, 0
	v_mov_b32_e32 v6, 0
	v_mov_b32_e32 v7, 0
	v_mov_b32_e32 v8, 0
	v_mov_b32_e32 v9, 0
	v_mov_b32_e32 v10, 0
	v_mov_b32_e32 v11, 0
	v_mov_b32_e32 v12, 0
	v_mov_b32_e32 v13, 0
	v_mov_b32_e32 v14, 0
	v_mov_b32_e32 v15, 0
	v_mov_b32_e32 v16, 0
	v_mov_b32_e32 v17, 0
	s_cbranch_vccnz .LBB0_421
	ds_read_b128 v[180:183], v124 offset:60416
	ds_read_b128 v[184:187], v120
	ds_read_b128 v[188:191], v124 offset:60448
	ds_read_b128 v[192:195], v120 offset:32
	ds_read_b128 v[196:199], v124 offset:60480
	ds_read_b128 v[200:203], v120 offset:64
	ds_read_b128 v[204:207], v124 offset:60512
	ds_read_b128 v[208:211], v120 offset:96
	ds_read_b128 v[212:215], v124 offset:60544
	ds_read_b128 v[216:219], v120 offset:128
	ds_read_b128 v[220:223], v124 offset:60576
	ds_read_b128 v[224:227], v120 offset:160
	ds_read_b128 v[228:231], v124 offset:60608
	ds_read_b128 v[232:235], v120 offset:192
	ds_read_b128 v[236:239], v124 offset:60640
	ds_read_b128 v[240:243], v120 offset:224
	s_waitcnt lgkmcnt(14)
	v_mfma_f32_32x32x16_bf16 v[2:17], v[180:183], v[184:187], 0
	s_waitcnt lgkmcnt(12)
	v_mfma_f32_32x32x16_bf16 v[2:17], v[188:191], v[192:195], v[2:17]
	s_waitcnt lgkmcnt(10)
	v_mfma_f32_32x32x16_bf16 v[2:17], v[196:199], v[200:203], v[2:17]
	s_waitcnt lgkmcnt(8)
	v_mfma_f32_32x32x16_bf16 v[2:17], v[204:207], v[208:211], v[2:17]
	s_waitcnt lgkmcnt(6)
	v_mfma_f32_32x32x16_bf16 v[2:17], v[212:215], v[216:219], v[2:17]
	s_waitcnt lgkmcnt(4)
	v_mfma_f32_32x32x16_bf16 v[2:17], v[220:223], v[224:227], v[2:17]
	s_waitcnt lgkmcnt(2)
	v_mfma_f32_32x32x16_bf16 v[2:17], v[228:231], v[232:235], v[2:17]
	s_waitcnt lgkmcnt(0)
	v_mfma_f32_32x32x16_bf16 v[2:17], v[236:239], v[240:243], v[2:17]
	s_branch .LBB0_421
